# DPP row_newbcast instead of ds_bpermute for the mLSTM denominator broadcast; gate-GEMV 64-lane sums via DPP + permlane swaps (no LDS round trips)
# speedup vs baseline: 1.0027x; 1.0027x over previous
.Lgate_nopf:
	v_and_b32_e32 v63, 0xffff0000, v58
	v_and_b32_e32 v85, 0xffff0000, v59
	v_and_b32_e32 v89, 0xffff0000, v60
	v_and_b32_e32 v91, 0xffff0000, v61
	v_and_b32_e32 v94, 0xffff0000, v72
	v_and_b32_e32 v98, 0xffff0000, v73
	v_and_b32_e32 v100, 0xffff0000, v74
	v_and_b32_e32 v104, 0xffff0000, v75
	v_and_b32_e32 v62, 16, v58
	v_lshlrev_b32_e32 v58, 16, v58
	v_and_b32_e32 v84, 16, v59
	v_lshlrev_b32_e32 v86, 16, v59
	v_and_b32_e32 v88, 16, v60
	v_lshlrev_b32_e32 v60, 16, v60
	v_and_b32_e32 v90, 16, v61
	v_lshlrev_b32_e32 v92, 16, v61
	v_and_b32_e32 v95, 16, v72
	v_lshlrev_b32_e32 v97, 16, v72
	v_and_b32_e32 v99, 16, v73
	v_lshlrev_b32_e32 v73, 16, v73
	v_and_b32_e32 v101, 16, v74
	v_lshlrev_b32_e32 v103, 16, v74
	v_and_b32_e32 v105, 16, v75
	v_lshlrev_b32_e32 v75, 16, v75
	v_mov_b32_e32 v59, v63
	v_mov_b32_e32 v87, v85
	v_mov_b32_e32 v61, v89
	v_mov_b32_e32 v93, v91
	v_mov_b32_e32 v96, v94
	v_mov_b32_e32 v72, v98
	v_mov_b32_e32 v102, v100
	v_mov_b32_e32 v74, v104
	v_pk_mul_f32 v[110:111], v[202:203], v[58:59]
	v_pk_mov_b32 v[62:63], v[62:63], v[58:59] op_sel:[1,0]
	v_pk_mul_f32 v[112:113], v[204:205], v[86:87]
	v_pk_mov_b32 v[84:85], v[84:85], v[86:87] op_sel:[1,0]
	v_pk_mul_f32 v[114:115], v[198:199], v[60:61]
	v_pk_mov_b32 v[88:89], v[88:89], v[60:61] op_sel:[1,0]
	v_pk_mul_f32 v[116:117], v[200:201], v[92:93]
	v_pk_mov_b32 v[90:91], v[90:91], v[92:93] op_sel:[1,0]
	v_pk_mov_b32 v[94:95], v[96:97], v[94:95] op_sel:[1,0]
	v_pk_mov_b32 v[98:99], v[72:73], v[98:99] op_sel:[1,0]
	v_pk_mov_b32 v[100:101], v[102:103], v[100:101] op_sel:[1,0]
	v_pk_mov_b32 v[104:105], v[74:75], v[104:105] op_sel:[1,0]
	v_pk_fma_f32 v[110:111], v[52:53], v[62:63], v[110:111]
	v_pk_fma_f32 v[112:113], v[54:55], v[84:85], v[112:113]
	v_pk_mul_f32 v[62:63], v[68:69], v[62:63]
	v_pk_mul_f32 v[84:85], v[70:71], v[84:85]
	v_pk_fma_f32 v[114:115], v[44:45], v[88:89], v[114:115]
	v_pk_fma_f32 v[116:117], v[46:47], v[90:91], v[116:117]
	v_pk_mul_f32 v[88:89], v[64:65], v[88:89]
	v_pk_mul_f32 v[90:91], v[66:67], v[90:91]
	v_pk_mul_f32 v[118:119], v[0:1], v[94:95]
	v_pk_mul_f32 v[94:95], v[16:17], v[94:95]
	v_pk_mul_f32 v[120:121], v[2:3], v[98:99]
	v_pk_mul_f32 v[98:99], v[18:19], v[98:99]
	v_pk_mul_f32 v[122:123], v[4:5], v[100:101]
	v_pk_mul_f32 v[124:125], v[6:7], v[104:105]
	v_pk_mul_f32 v[100:101], v[20:21], v[100:101]
	v_pk_add_f32 v[110:111], v[110:111], v[112:113]
	v_pk_fma_f32 v[58:59], v[178:179], v[58:59], v[62:63]
	v_pk_fma_f32 v[62:63], v[180:181], v[86:87], v[84:85]
	v_pk_add_f32 v[84:85], v[114:115], v[116:117]
	v_pk_fma_f32 v[60:61], v[174:175], v[60:61], v[88:89]
	v_pk_fma_f32 v[86:87], v[176:177], v[92:93], v[90:91]
	v_pk_fma_f32 v[88:89], v[196:197], v[96:97], v[118:119]
	v_pk_fma_f32 v[90:91], v[172:173], v[96:97], v[94:95]
	v_pk_fma_f32 v[92:93], v[194:195], v[72:73], v[120:121]
	v_pk_fma_f32 v[72:73], v[170:171], v[72:73], v[98:99]
	v_pk_fma_f32 v[94:95], v[192:193], v[102:103], v[122:123]
	v_pk_fma_f32 v[98:99], v[190:191], v[74:75], v[124:125]
	v_and_b32_e32 v106, 0xffff0000, v76
	v_pk_mul_f32 v[104:105], v[22:23], v[104:105]
	v_pk_fma_f32 v[96:97], v[168:169], v[102:103], v[100:101]
	v_and_b32_e32 v100, 0xffff0000, v77
	v_pk_add_f32 v[84:85], v[110:111], v[84:85]
	v_pk_add_f32 v[88:89], v[88:89], v[92:93]
	v_pk_add_f32 v[92:93], v[94:95], v[98:99]
	v_and_b32_e32 v107, 16, v76
	v_lshlrev_b32_e32 v109, 16, v76
	v_pk_fma_f32 v[74:75], v[166:167], v[74:75], v[104:105]
	v_pk_add_f32 v[58:59], v[58:59], v[62:63]
	v_pk_add_f32 v[60:61], v[60:61], v[86:87]
	v_mov_b32_e32 v108, v106
	v_and_b32_e32 v101, 16, v77
	v_lshlrev_b32_e32 v77, 16, v77
	v_mov_b32_e32 v76, v100
	v_pk_add_f32 v[84:85], v[84:85], 0 op_sel_hi:[1,0]
	v_pk_add_f32 v[88:89], v[88:89], v[92:93]
	v_pk_mul_f32 v[62:63], v[188:189], v[108:109]
	v_pk_mul_f32 v[102:103], v[186:187], v[76:77]
	v_pk_mul_f32 v[104:105], v[162:163], v[76:77]
	v_and_b32_e32 v112, 0xffff0000, v78
	v_and_b32_e32 v120, 0xffff0000, v79
	v_pk_add_f32 v[84:85], v[84:85], v[88:89]
	v_pk_mov_b32 v[88:89], v[108:109], v[106:107] op_sel:[1,0]
	v_pk_mov_b32 v[76:77], v[76:77], v[100:101] op_sel:[1,0]
	v_pk_add_f32 v[58:59], v[58:59], v[60:61]
	v_pk_add_f32 v[60:61], v[90:91], v[72:73]
	v_pk_add_f32 v[72:73], v[96:97], v[74:75]
	v_pk_mul_f32 v[86:87], v[164:165], v[108:109]
	v_and_b32_e32 v113, 16, v78
	v_lshlrev_b32_e32 v115, 16, v78
	v_mov_b32_e32 v114, v112
	v_and_b32_e32 v121, 16, v79
	v_lshlrev_b32_e32 v79, 16, v79
	v_mov_b32_e32 v78, v120
	v_pk_fma_f32 v[62:63], v[8:9], v[88:89], v[62:63]
	v_pk_fma_f32 v[92:93], v[10:11], v[76:77], v[102:103]
	v_pk_add_f32 v[58:59], v[58:59], 0 op_sel_hi:[1,0]
	v_pk_add_f32 v[60:61], v[60:61], v[72:73]
	v_pk_mul_f32 v[116:117], v[184:185], v[114:115]
	v_pk_mul_f32 v[118:119], v[160:161], v[114:115]
	v_pk_mul_f32 v[122:123], v[182:183], v[78:79]
	v_pk_mul_f32 v[124:125], v[158:159], v[78:79]
	v_pk_add_f32 v[62:63], v[62:63], v[92:93]
	v_pk_mov_b32 v[92:93], v[114:115], v[112:113] op_sel:[1,0]
	v_pk_mov_b32 v[78:79], v[78:79], v[120:121] op_sel:[1,0]
	v_pk_add_f32 v[58:59], v[58:59], v[60:61] op_sel:[1,0] op_sel_hi:[0,1]
	v_pk_fma_f32 v[60:61], v[24:25], v[88:89], v[86:87]
	v_pk_fma_f32 v[72:73], v[26:27], v[76:77], v[104:105]
	v_pk_fma_f32 v[94:95], v[12:13], v[92:93], v[116:117]
	v_pk_fma_f32 v[98:99], v[14:15], v[78:79], v[122:123]
	v_pk_add_f32 v[60:61], v[60:61], v[72:73]
	v_pk_fma_f32 v[72:73], v[28:29], v[92:93], v[118:119]
	v_pk_fma_f32 v[74:75], v[30:31], v[78:79], v[124:125]
	v_pk_add_f32 v[94:95], v[94:95], v[98:99]
	v_pk_add_f32 v[72:73], v[72:73], v[74:75]
	v_lshlrev_b32_e32 v126, 16, v80
	v_and_b32_e32 v127, 0xffff0000, v80
	v_lshlrev_b32_e32 v80, 16, v81
	v_and_b32_e32 v81, 0xffff0000, v81
	v_pk_add_f32 v[62:63], v[62:63], v[94:95]
	v_pk_add_f32 v[60:61], v[60:61], v[72:73]
	v_pk_add_f32 v[62:63], v[84:85], v[62:63]
	v_pk_mul_f32 v[84:85], v[32:33], v[126:127] op_sel:[0,1] op_sel_hi:[1,0]
	v_pk_mul_f32 v[94:95], v[34:35], v[80:81] op_sel:[0,1] op_sel_hi:[1,0]
	v_pk_add_f32 v[58:59], v[58:59], v[60:61]
	v_pk_mul_f32 v[60:61], v[40:41], v[126:127] op_sel:[0,1] op_sel_hi:[1,0]
	v_pk_mul_f32 v[72:73], v[42:43], v[80:81] op_sel:[0,1] op_sel_hi:[1,0]
	v_lshlrev_b32_e32 v228, 16, v82
	v_and_b32_e32 v229, 0xffff0000, v82
	v_lshlrev_b32_e32 v82, 16, v83
	v_and_b32_e32 v83, 0xffff0000, v83
	v_pk_fma_f32 v[84:85], v[142:143], v[126:127], v[84:85]
	v_pk_fma_f32 v[94:95], v[144:145], v[80:81], v[94:95]
	v_pk_fma_f32 v[60:61], v[150:151], v[126:127], v[60:61]
	v_pk_fma_f32 v[72:73], v[152:153], v[80:81], v[72:73]
	v_pk_add_f32 v[84:85], v[84:85], v[94:95]
	v_pk_mul_f32 v[94:95], v[36:37], v[228:229] op_sel:[0,1] op_sel_hi:[1,0]
	v_pk_mul_f32 v[98:99], v[38:39], v[82:83] op_sel:[0,1] op_sel_hi:[1,0]
	v_pk_add_f32 v[60:61], v[60:61], v[72:73]
	v_pk_mul_f32 v[72:73], v[48:49], v[228:229] op_sel:[0,1] op_sel_hi:[1,0]
	v_pk_mul_f32 v[74:75], v[50:51], v[82:83] op_sel:[0,1] op_sel_hi:[1,0]
	v_pk_fma_f32 v[94:95], v[146:147], v[228:229], v[94:95]
	v_pk_fma_f32 v[98:99], v[148:149], v[82:83], v[98:99]
	v_pk_fma_f32 v[72:73], v[154:155], v[228:229], v[72:73]
	v_pk_fma_f32 v[74:75], v[156:157], v[82:83], v[74:75]
	v_pk_add_f32 v[94:95], v[94:95], v[98:99]
	v_pk_add_f32 v[72:73], v[72:73], v[74:75]
	v_pk_add_f32 v[84:85], v[84:85], v[94:95]
	v_pk_add_f32 v[60:61], v[60:61], v[72:73]
	v_pk_add_f32 v[62:63], v[62:63], v[84:85]
	v_pk_add_f32 v[58:59], v[58:59], v[60:61]
	s_nop 1
	v_add_f32_dpp v62, v62, v62 quad_perm:[1,0,3,2] row_mask:0xf bank_mask:0xf
	v_add_f32_dpp v63, v63, v63 quad_perm:[1,0,3,2] row_mask:0xf bank_mask:0xf
	v_add_f32_dpp v58, v58, v58 quad_perm:[1,0,3,2] row_mask:0xf bank_mask:0xf
	v_add_f32_dpp v59, v59, v59 quad_perm:[1,0,3,2] row_mask:0xf bank_mask:0xf
	v_add_f32_dpp v62, v62, v62 quad_perm:[2,3,0,1] row_mask:0xf bank_mask:0xf
	v_add_f32_dpp v63, v63, v63 quad_perm:[2,3,0,1] row_mask:0xf bank_mask:0xf
	v_add_f32_dpp v58, v58, v58 quad_perm:[2,3,0,1] row_mask:0xf bank_mask:0xf
	v_add_f32_dpp v59, v59, v59 quad_perm:[2,3,0,1] row_mask:0xf bank_mask:0xf
	v_add_f32_dpp v62, v62, v62 row_half_mirror row_mask:0xf bank_mask:0xf
	v_add_f32_dpp v63, v63, v63 row_half_mirror row_mask:0xf bank_mask:0xf
	v_add_f32_dpp v58, v58, v58 row_half_mirror row_mask:0xf bank_mask:0xf
	v_add_f32_dpp v59, v59, v59 row_half_mirror row_mask:0xf bank_mask:0xf
	v_add_f32_dpp v62, v62, v62 row_mirror row_mask:0xf bank_mask:0xf
	v_add_f32_dpp v63, v63, v63 row_mirror row_mask:0xf bank_mask:0xf
	v_add_f32_dpp v58, v58, v58 row_mirror row_mask:0xf bank_mask:0xf
	v_add_f32_dpp v59, v59, v59 row_mirror row_mask:0xf bank_mask:0xf
	v_mov_b32_e32 v84, v62
	v_mov_b32_e32 v85, v63
	v_mov_b32_e32 v86, v58
	v_mov_b32_e32 v87, v59
	v_permlane16_swap_b32_e32 v62, v84
	v_permlane16_swap_b32_e32 v63, v85
	v_permlane16_swap_b32_e32 v58, v86
	v_permlane16_swap_b32_e32 v59, v87
	v_add_f32_e32 v62, v62, v84
	v_add_f32_e32 v63, v63, v85
	v_add_f32_e32 v58, v58, v86
	v_add_f32_e32 v59, v59, v87
	v_mov_b32_e32 v84, v62
	v_mov_b32_e32 v85, v63
	v_mov_b32_e32 v86, v58
	v_mov_b32_e32 v87, v59
	v_permlane32_swap_b32_e32 v62, v84
	v_permlane32_swap_b32_e32 v63, v85
	v_permlane32_swap_b32_e32 v58, v86
	v_permlane32_swap_b32_e32 v59, v87
	v_add_f32_e32 v62, v62, v84
	v_add_f32_e32 v63, v63, v85
	v_add_f32_e32 v58, v58, v86
	v_add_f32_e32 v59, v59, v87
	s_and_saveexec_b64 s[8:9], s[2:3]
	s_cbranch_execz .LBB0_399
	v_mov_b32_e32 v84, v63
	v_mov_b32_e32 v85, v62
	v_mov_b32_e32 v86, v59
	v_mov_b32_e32 v87, v58
	v_mov_b32_e32 v88, s12
	ds_write_b128 v88, v[84:87]
	s_branch .LBB0_399

.LBB0_463:
	global_load_dword v207, v73, s[38:39] offset:32
	s_add_u32 s36, s36, s40
	s_addc_u32 s37, s37, s57
	s_add_u32 s38, s38, s41
	s_addc_u32 s39, s39, s57
	s_waitcnt lgkmcnt(0)
	s_barrier
	ds_read_b128 v[226:229], v187
	v_add_u32_e32 v46, v79, v167
	ds_read_b128 v[230:233], v46
	ds_read_b128 v[234:237], v80
	s_waitcnt lgkmcnt(1)
	v_mfma_f32_16x16x32_bf16 v[230:233], v[226:229], v[230:233], 0
	global_load_dword v113, v89, s[52:53]
	s_waitcnt lgkmcnt(0)
	v_mfma_f32_16x16x32_bf16 v[226:229], v[226:229], v[234:237], 0
	global_load_dword v114, v89, s[52:53] offset:2048
	ds_read_b128 v[234:237], v187 offset:64
	ds_read_b128 v[238:241], v46 offset:64
	s_waitcnt lgkmcnt(0)
	v_mfma_f32_16x16x32_bf16 v[230:233], v[234:237], v[238:241], v[230:233]
	global_load_dword v115, v89, s[54:55]
	ds_read_b128 v[238:241], v80 offset:64
	s_waitcnt lgkmcnt(0)
	v_mfma_f32_16x16x32_bf16 v[226:229], v[234:237], v[238:241], v[226:229]
	global_load_dword v116, v89, s[54:55] offset:2048
	ds_read_b128 v[234:237], v187 offset:128
	ds_read_b128 v[238:241], v46 offset:128
	s_waitcnt lgkmcnt(0)
	v_mfma_f32_16x16x32_bf16 v[230:233], v[234:237], v[238:241], v[230:233]
	global_load_dword v117, v90, s[52:53]
	ds_read_b128 v[238:241], v80 offset:128
	s_waitcnt lgkmcnt(0)
	v_mfma_f32_16x16x32_bf16 v[226:229], v[234:237], v[238:241], v[226:229]
	global_load_dword v118, v90, s[52:53] offset:2048
	ds_read_b128 v[234:237], v187 offset:192
	ds_read_b128 v[238:241], v46 offset:192
	s_waitcnt lgkmcnt(0)
	v_mfma_f32_16x16x32_bf16 v[230:233], v[234:237], v[238:241], v[230:233]
	global_load_dword v119, v90, s[54:55]
	ds_read_b128 v[238:241], v80 offset:192
	s_waitcnt lgkmcnt(0)
	v_mfma_f32_16x16x32_bf16 v[226:229], v[234:237], v[238:241], v[226:229]
	global_load_dword v120, v90, s[54:55] offset:2048
	ds_read_b128 v[234:237], v187 offset:256
	ds_read_b128 v[238:241], v46 offset:256
	s_waitcnt lgkmcnt(0)
	v_mfma_f32_16x16x32_bf16 v[230:233], v[234:237], v[238:241], v[230:233]
	global_load_dword v121, v91, s[52:53]
	ds_read_b128 v[238:241], v80 offset:256
	s_waitcnt lgkmcnt(0)
	v_mfma_f32_16x16x32_bf16 v[226:229], v[234:237], v[238:241], v[226:229]
	global_load_dword v122, v91, s[52:53] offset:2048
	ds_read_b128 v[234:237], v187 offset:320
	ds_read_b128 v[238:241], v46 offset:320
	s_waitcnt lgkmcnt(0)
	v_mfma_f32_16x16x32_bf16 v[230:233], v[234:237], v[238:241], v[230:233]
	global_load_dword v123, v91, s[54:55]
	ds_read_b128 v[238:241], v80 offset:320
	s_waitcnt lgkmcnt(0)
	v_mfma_f32_16x16x32_bf16 v[226:229], v[234:237], v[238:241], v[226:229]
	global_load_dword v124, v91, s[54:55] offset:2048
	ds_read_b128 v[234:237], v187 offset:384
	ds_read_b128 v[238:241], v46 offset:384
	s_waitcnt lgkmcnt(0)
	v_mfma_f32_16x16x32_bf16 v[230:233], v[234:237], v[238:241], v[230:233]
	global_load_dword v125, v92, s[52:53]
	ds_read_b128 v[238:241], v80 offset:384
	s_waitcnt lgkmcnt(0)
	v_mfma_f32_16x16x32_bf16 v[226:229], v[234:237], v[238:241], v[226:229]
	global_load_dword v126, v92, s[52:53] offset:2048
	ds_read_b128 v[234:237], v187 offset:448
	ds_read_b128 v[238:241], v46 offset:448
	s_waitcnt lgkmcnt(0)
	v_mfma_f32_16x16x32_bf16 v[230:233], v[234:237], v[238:241], v[230:233]
	global_load_dword v134, v92, s[54:55]
	ds_read_b128 v[238:241], v80 offset:448
	s_waitcnt lgkmcnt(0)
	v_mfma_f32_16x16x32_bf16 v[226:229], v[234:237], v[238:241], v[226:229]
	global_load_dword v135, v92, s[54:55] offset:2048
	ds_bpermute_b32 v46, v176, v48
	v_add_u32_e32 v206, v77, v75
	v_add_u32_e32 v217, s18, v183
	s_waitcnt lgkmcnt(0)
	v_mul_f32_e32 v46, 0x3fb8aa3b, v46
	v_exp_f32_e32 v218, v46
	ds_bpermute_b32 v46, v177, v48
	s_waitcnt lgkmcnt(0)
	v_mul_f32_e32 v46, 0x3fb8aa3b, v46
	v_exp_f32_e32 v219, v46
	ds_bpermute_b32 v46, v178, v48
	v_pk_mul_f32 v[226:227], v[226:227], v[218:219]
	s_waitcnt lgkmcnt(0)
	v_mul_f32_e32 v46, 0x3fb8aa3b, v46
	v_exp_f32_e32 v222, v46
	ds_bpermute_b32 v46, v179, v48
	s_waitcnt lgkmcnt(0)
	v_mul_f32_e32 v46, 0x3fb8aa3b, v46
	v_exp_f32_e32 v223, v46
	v_pk_mul_f32 v[46:47], v[230:231], v[218:219]
	v_add_u32_e32 v218, v168, v81
	ds_read_b128 v[234:237], v218
	v_pk_mul_f32 v[48:49], v[232:233], v[222:223]
	ds_read_b128 v[230:233], v188
	v_pk_mul_f32 v[228:229], v[228:229], v[222:223]
	v_add_u32_e32 v219, v168, v82
	v_add_u32_e32 v222, s26, v185
	s_waitcnt lgkmcnt(0)
	v_mfma_f32_16x16x32_bf16 v[46:49], v[230:233], v[234:237], v[46:49]
	global_load_dword v136, v93, s[52:53]
	ds_read_b128 v[234:237], v206
	s_waitcnt lgkmcnt(0)
	v_mfma_f32_16x16x32_bf16 v[226:229], v[230:233], v[234:237], v[226:229]
	global_load_dword v137, v93, s[52:53] offset:2048
	ds_read_b128 v[230:233], v188 offset:64
	ds_read_b128 v[234:237], v219
	s_waitcnt lgkmcnt(0)
	v_mfma_f32_16x16x32_bf16 v[46:49], v[230:233], v[234:237], v[46:49]
	global_load_dword v138, v93, s[54:55]
	ds_read_b128 v[234:237], v110
	s_waitcnt lgkmcnt(0)
	v_mfma_f32_16x16x32_bf16 v[226:229], v[230:233], v[234:237], v[226:229]
	global_load_dword v139, v93, s[54:55] offset:2048
	v_cndmask_b32_e64 v230, v222, v217, s[2:3]
	v_ashrrev_i32_e32 v231, 31, v230
	v_lshlrev_b64 v[230:231], 12, v[230:231]
	s_nop 4
	v_mov_b32_dpp v223, v226 row_newbcast:0 row_mask:0xf bank_mask:0xf
	v_lshl_add_u64 v[230:231], v[70:71], 0, v[230:231]
	s_waitcnt lgkmcnt(0)
	v_max_f32_e64 v223, |v223|, |v223|
	v_max_f32_e32 v223, 1.0, v223
	v_div_scale_f32 v225, s[16:17], v223, v223, v46
	v_rcp_f32_e32 v226, v225
	s_nop 0
	v_fma_f32 v232, -v225, v226, 1.0
	v_fmac_f32_e32 v226, v232, v226
	v_div_scale_f32 v232, vcc, v46, v223, v46
	v_mul_f32_e32 v233, v232, v226
	v_fma_f32 v234, -v225, v233, v232
	v_fmac_f32_e32 v233, v234, v226
	v_fma_f32 v225, -v225, v233, v232
	v_div_fmas_f32 v225, v225, v226, v233
	v_div_fixup_f32 v46, v225, v223, v46
	v_cvt_pk_bf16_f32 v46, v46, s0
	global_store_short v[230:231], v46, off offset:2048
	v_mov_b32_dpp v46, v227 row_newbcast:0 row_mask:0xf bank_mask:0xf
	v_add_u32_e32 v223, -1, v222
	v_add_u32_e32 v225, 1, v217
	v_cndmask_b32_e64 v226, v223, v225, s[2:3]
	v_ashrrev_i32_e32 v227, 31, v226
	s_waitcnt lgkmcnt(0)
	v_max_f32_e64 v46, |v46|, |v46|
	v_max_f32_e32 v46, 1.0, v46
	v_div_scale_f32 v223, s[16:17], v46, v46, v47
	v_rcp_f32_e32 v225, v223
	s_nop 0
	v_fma_f32 v230, -v223, v225, 1.0
	v_fmac_f32_e32 v225, v230, v225
	v_div_scale_f32 v230, vcc, v47, v46, v47
	v_mul_f32_e32 v231, v230, v225
	v_fma_f32 v232, -v223, v231, v230
	v_fmac_f32_e32 v231, v232, v225
	v_fma_f32 v223, -v223, v231, v230
	v_div_fmas_f32 v223, v223, v225, v231
	v_mov_b32_dpp v225, v228 row_newbcast:0 row_mask:0xf bank_mask:0xf
	v_div_fixup_f32 v46, v223, v46, v47
	v_cvt_pk_bf16_f32 v223, v46, s0
	v_lshlrev_b64 v[46:47], 12, v[226:227]
	v_lshl_add_u64 v[46:47], v[70:71], 0, v[46:47]
	s_waitcnt lgkmcnt(0)
	v_max_f32_e64 v225, |v225|, |v225|
	v_max_f32_e32 v225, 1.0, v225
	v_div_scale_f32 v226, s[16:17], v225, v225, v48
	v_rcp_f32_e32 v227, v226
	global_store_short v[46:47], v223, off offset:2048
	v_add_u32_e32 v223, s26, v184
	v_add_u32_e32 v46, 0xffd, v223
	v_fma_f32 v228, -v226, v227, 1.0
	v_fmac_f32_e32 v227, v228, v227
	v_div_scale_f32 v228, vcc, v48, v225, v48
	v_mul_f32_e32 v230, v228, v227
	v_fma_f32 v231, -v226, v230, v228
	v_add_u32_e32 v47, 2, v217
	v_fmac_f32_e32 v230, v231, v227
	v_cndmask_b32_e64 v46, v46, v47, s[2:3]
	v_fma_f32 v226, -v226, v230, v228
	v_ashrrev_i32_e32 v47, 31, v46
	v_div_fmas_f32 v226, v226, v227, v230
	v_div_fixup_f32 v48, v226, v225, v48
	v_lshlrev_b64 v[46:47], 12, v[46:47]
	v_cvt_pk_bf16_f32 v48, v48, s0
	v_lshl_add_u64 v[46:47], v[70:71], 0, v[46:47]
	global_store_short v[46:47], v48, off offset:2048
	v_mov_b32_dpp v48, v229 row_newbcast:0 row_mask:0xf bank_mask:0xf
	v_add_u32_e32 v46, 0xffc, v223
	v_add_u32_e32 v47, 3, v217
	v_cndmask_b32_e64 v46, v46, v47, s[2:3]
	v_ashrrev_i32_e32 v47, 31, v46
	s_waitcnt lgkmcnt(0)
	v_max_f32_e64 v48, |v48|, |v48|
	v_max_f32_e32 v48, 1.0, v48
	v_div_scale_f32 v225, s[16:17], v48, v48, v49
	v_rcp_f32_e32 v226, v225
	v_lshlrev_b64 v[46:47], 12, v[46:47]
	v_lshl_add_u64 v[46:47], v[70:71], 0, v[46:47]
	v_fma_f32 v227, -v225, v226, 1.0
	v_fmac_f32_e32 v226, v227, v226
	v_div_scale_f32 v227, vcc, v49, v48, v49
	v_mul_f32_e32 v228, v227, v226
	v_fma_f32 v229, -v225, v228, v227
	v_fmac_f32_e32 v228, v229, v226
	v_fma_f32 v225, -v225, v228, v227
	v_div_fmas_f32 v225, v225, v226, v228
	v_div_fixup_f32 v48, v225, v48, v49
	v_cvt_pk_bf16_f32 v48, v48, s0
	global_store_short v[46:47], v48, off offset:2048
	v_mul_f32_e32 v46, 0x3fb8aa3b, v224
	v_add_u32_e32 v224, v0, v81
	v_exp_f32_e32 v46, v46
	ds_read_b128 v[226:229], v224 offset:33792
	ds_read_b128 v[230:233], v111
	v_add_u32_e32 v49, v0, v82
	v_add_u32_e32 v225, v84, v82
	v_pk_mul_f32 v[44:45], v[44:45], v[46:47] op_sel_hi:[1,0]
	v_pk_mul_f32 v[42:43], v[42:43], v[46:47] op_sel_hi:[1,0]
	v_pk_mul_f32 v[40:41], v[40:41], v[46:47] op_sel_hi:[1,0]
	v_pk_mul_f32 v[38:39], v[38:39], v[46:47] op_sel_hi:[1,0]
	s_waitcnt lgkmcnt(0)
	v_mfma_f32_16x16x32_bf16 v[42:45], v[226:229], v[230:233], v[42:45]
	global_load_dword v140, v94, s[52:53]
	ds_read_b128 v[226:229], v49 offset:33792
	ds_read_b128 v[230:233], v225
	v_pk_mul_f32 v[36:37], v[36:37], v[46:47] op_sel_hi:[1,0]
	s_waitcnt lgkmcnt(0)
	v_mfma_f32_16x16x32_bf16 v[42:45], v[226:229], v[230:233], v[42:45]
	global_load_dword v141, v94, s[52:53] offset:2048
	v_mul_f32_e64 v34, v34, v46
	v_mul_f32_e64 v35, v35, v46
	s_nop 5
	v_cvt_pk_bf16_f32 v226, v42, v43
	v_cvt_pk_bf16_f32 v227, v44, v45
	ds_write_b64 v189, v[226:227] offset:17952
	v_add_u32_e32 v226, v86, v81
	ds_read_b128 v[228:231], v49 offset:33792
	ds_read_b128 v[232:235], v224 offset:33792
	ds_read_b128 v[236:239], v226
	v_add_u32_e32 v227, v86, v82
	s_waitcnt lgkmcnt(0)
	v_mfma_f32_16x16x32_bf16 v[38:41], v[232:235], v[236:239], v[38:41]
	global_load_dword v142, v94, s[54:55]
	ds_read_b128 v[232:235], v227
	s_waitcnt lgkmcnt(0)
	v_mfma_f32_16x16x32_bf16 v[38:41], v[228:231], v[232:235], v[38:41]
	global_load_dword v143, v94, s[54:55] offset:2048
	s_nop 7
	v_cvt_pk_bf16_f32 v228, v38, v39
	v_cvt_pk_bf16_f32 v229, v40, v41
	ds_write_b64 v189, v[228:229] offset:26400
	ds_read_b128 v[228:231], v49 offset:33792
	ds_read_b128 v[232:235], v224 offset:33792
	ds_read_b128 v[236:239], v206
	s_waitcnt lgkmcnt(0)
	v_mfma_f32_16x16x32_bf16 v[34:37], v[232:235], v[236:239], v[34:37]
	global_load_dword v144, v95, s[52:53]
	ds_read_b128 v[232:235], v110
	s_waitcnt lgkmcnt(0)
	v_mfma_f32_16x16x32_bf16 v[34:37], v[228:231], v[232:235], v[34:37]
	global_load_dword v145, v95, s[52:53] offset:2048
	s_and_saveexec_b64 s[16:17], s[0:1]
	s_nop 6
	v_cvt_pk_bf16_f32 v228, v34, v35
	v_cvt_pk_bf16_f32 v229, v36, v37
	ds_write_b64 v172, v[228:229] offset:34848
	s_or_b64 exec, exec, s[16:17]
	ds_read_b128 v[228:231], v224 offset:36096
	ds_read_b128 v[232:235], v111
	ds_read_b128 v[236:239], v49 offset:36096
	v_mov_b32_e32 v47, v46
	v_mov_b32_e32 v240, v46
	v_mov_b32_e32 v241, v46
	v_pk_mul_f32 v[28:29], v[28:29], v[240:241]
	v_pk_mul_f32 v[26:27], v[26:27], v[46:47]
	v_pk_mul_f32 v[32:33], v[32:33], v[240:241]
	v_pk_mul_f32 v[30:31], v[30:31], v[46:47]
	s_waitcnt lgkmcnt(1)
	v_mfma_f32_16x16x32_bf16 v[26:29], v[228:231], v[232:235], v[26:29]
	global_load_dword v146, v95, s[54:55]
	ds_read_b128 v[228:231], v225
	v_pk_mul_f32 v[24:25], v[24:25], v[240:241]
	v_pk_mul_f32 v[22:23], v[22:23], v[46:47]
	s_waitcnt lgkmcnt(0)
	v_mfma_f32_16x16x32_bf16 v[26:29], v[236:239], v[228:231], v[26:29]
	global_load_dword v147, v95, s[54:55] offset:2048
	s_nop 7
	v_cvt_pk_bf16_f32 v228, v26, v27
	v_cvt_pk_bf16_f32 v229, v28, v29
	ds_write_b64 v189, v[228:229] offset:17984
	ds_read_b128 v[228:231], v224 offset:36096
	ds_read_b128 v[232:235], v226
	ds_read_b128 v[236:239], v227
	s_waitcnt lgkmcnt(1)
	v_mfma_f32_16x16x32_bf16 v[30:33], v[228:231], v[232:235], v[30:33]
	global_load_dword v149, v96, s[52:53]
	ds_read_b128 v[228:231], v49 offset:36096
	s_waitcnt lgkmcnt(0)
	v_mfma_f32_16x16x32_bf16 v[30:33], v[228:231], v[236:239], v[30:33]
	global_load_dword v150, v96, s[52:53] offset:2048
	s_nop 7
	v_cvt_pk_bf16_f32 v228, v30, v31
	v_cvt_pk_bf16_f32 v229, v32, v33
	ds_write_b64 v189, v[228:229] offset:26432
	ds_read_b128 v[228:231], v224 offset:36096
	ds_read_b128 v[232:235], v206
	ds_read_b128 v[236:239], v110
	s_waitcnt lgkmcnt(1)
	v_mfma_f32_16x16x32_bf16 v[22:25], v[228:231], v[232:235], v[22:25]
	global_load_dword v155, v96, s[54:55]
	ds_read_b128 v[228:231], v49 offset:36096
	s_waitcnt lgkmcnt(0)
	v_mfma_f32_16x16x32_bf16 v[22:25], v[228:231], v[236:239], v[22:25]
	global_load_dword v156, v96, s[54:55] offset:2048
	s_add_u32 s52, s52, s56
	s_addc_u32 s53, s53, s57
	s_add_u32 s54, s54, s56
	s_addc_u32 s55, s55, s57
	s_and_saveexec_b64 s[16:17], s[0:1]
	s_nop 6
	v_cvt_pk_bf16_f32 v46, v22, v23
	v_cvt_pk_bf16_f32 v47, v24, v25
	ds_write_b64 v172, v[46:47] offset:34880
	s_or_b64 exec, exec, s[16:17]
	s_waitcnt vmcnt(36)
	ds_bpermute_b32 v228, v109, v207
	s_waitcnt lgkmcnt(0)
	s_barrier
	s_and_b64 vcc, exec, s[4:5]
	s_cbranch_vccnz .LBB0_469
	v_cvt_pk_bf16_f32 v46, v148, s0
	ds_write_b16 v72, v46 offset:4608

.LBB0_480:
	s_waitcnt lgkmcnt(0)
	s_barrier
	ds_read_b128 v[208:211], v187
	v_add_u32_e32 v46, v87, v167
	ds_read_b128 v[212:215], v46
	ds_read_b128 v[230:233], v187 offset:64
	ds_read_b128 v[234:237], v46 offset:64
	ds_read_b128 v[238:241], v88
	ds_read_b128 v[242:245], v88 offset:64
	s_waitcnt lgkmcnt(4)
	v_mfma_f32_16x16x32_bf16 v[212:215], v[208:211], v[212:215], 0
	global_load_dword v151, v89, s[52:53]
	s_waitcnt lgkmcnt(1)
	v_mfma_f32_16x16x32_bf16 v[208:211], v[208:211], v[238:241], 0
	global_load_dword v152, v89, s[52:53] offset:2048
	v_mfma_f32_16x16x32_bf16 v[212:215], v[230:233], v[234:237], v[212:215]
	global_load_dword v153, v89, s[54:55]
	s_waitcnt lgkmcnt(0)
	v_mfma_f32_16x16x32_bf16 v[208:211], v[230:233], v[242:245], v[208:211]
	global_load_dword v154, v89, s[54:55] offset:2048
	ds_read_b128 v[230:233], v187 offset:128
	ds_read_b128 v[234:237], v46 offset:128
	ds_read_b128 v[238:241], v46 offset:192
	ds_read_b128 v[242:245], v187 offset:192
	s_waitcnt lgkmcnt(2)
	v_mfma_f32_16x16x32_bf16 v[212:215], v[230:233], v[234:237], v[212:215]
	global_load_dword v157, v90, s[52:53]
	ds_read_b128 v[234:237], v88 offset:128
	ds_read_b128 v[246:249], v88 offset:192
	s_waitcnt lgkmcnt(1)
	v_mfma_f32_16x16x32_bf16 v[208:211], v[230:233], v[234:237], v[208:211]
	global_load_dword v158, v90, s[52:53] offset:2048
	v_mfma_f32_16x16x32_bf16 v[212:215], v[242:245], v[238:241], v[212:215]
	global_load_dword v159, v90, s[54:55]
	s_waitcnt lgkmcnt(0)
	v_mfma_f32_16x16x32_bf16 v[208:211], v[242:245], v[246:249], v[208:211]
	global_load_dword v160, v90, s[54:55] offset:2048
	ds_read_b128 v[230:233], v187 offset:256
	ds_read_b128 v[234:237], v46 offset:256
	ds_read_b128 v[238:241], v46 offset:320
	ds_read_b128 v[242:245], v187 offset:320
	s_waitcnt lgkmcnt(2)
	v_mfma_f32_16x16x32_bf16 v[212:215], v[230:233], v[234:237], v[212:215]
	global_load_dword v161, v91, s[52:53]
	ds_read_b128 v[234:237], v88 offset:256
	ds_read_b128 v[246:249], v88 offset:320
	s_waitcnt lgkmcnt(1)
	v_mfma_f32_16x16x32_bf16 v[208:211], v[230:233], v[234:237], v[208:211]
	global_load_dword v162, v91, s[52:53] offset:2048
	v_mfma_f32_16x16x32_bf16 v[212:215], v[242:245], v[238:241], v[212:215]
	global_load_dword v164, v91, s[54:55]
	s_waitcnt lgkmcnt(0)
	v_mfma_f32_16x16x32_bf16 v[208:211], v[242:245], v[246:249], v[208:211]
	global_load_dword v165, v91, s[54:55] offset:2048
	ds_read_b128 v[230:233], v187 offset:384
	ds_read_b128 v[234:237], v46 offset:384
	ds_read_b128 v[238:241], v46 offset:448
	ds_read_b128 v[242:245], v187 offset:448
	s_waitcnt lgkmcnt(2)
	v_mfma_f32_16x16x32_bf16 v[212:215], v[230:233], v[234:237], v[212:215]
	global_load_dword v169, v92, s[52:53]
	ds_read_b128 v[234:237], v88 offset:384
	ds_read_b128 v[246:249], v88 offset:448
	s_waitcnt lgkmcnt(1)
	v_mfma_f32_16x16x32_bf16 v[208:211], v[230:233], v[234:237], v[208:211]
	global_load_dword v171, v92, s[52:53] offset:2048
	v_mfma_f32_16x16x32_bf16 v[212:215], v[242:245], v[238:241], v[212:215]
	global_load_dword v180, v92, s[54:55]
	s_waitcnt lgkmcnt(0)
	v_mfma_f32_16x16x32_bf16 v[208:211], v[242:245], v[246:249], v[208:211]
	global_load_dword v181, v92, s[54:55] offset:2048
	ds_bpermute_b32 v46, v176, v207
	ds_bpermute_b32 v47, v177, v207
	ds_bpermute_b32 v216, v178, v207
	ds_bpermute_b32 v207, v179, v207
	ds_read_b128 v[230:233], v188
	ds_read_b128 v[234:237], v218
	s_waitcnt lgkmcnt(5)
	v_mul_f32_e32 v46, 0x3fb8aa3b, v46
	s_waitcnt lgkmcnt(4)
	v_mul_f32_e32 v47, 0x3fb8aa3b, v47
	s_waitcnt lgkmcnt(3)
	v_mul_f32_e32 v216, 0x3fb8aa3b, v216
	s_waitcnt lgkmcnt(2)
	v_mul_f32_e32 v207, 0x3fb8aa3b, v207
	v_exp_f32_e32 v46, v46
	v_exp_f32_e32 v47, v47
	v_exp_f32_e32 v246, v216
	v_exp_f32_e32 v247, v207
	ds_read_b128 v[238:241], v206
	ds_read_b128 v[242:245], v188 offset:64
	v_pk_mul_f32 v[212:213], v[212:213], v[46:47]
	v_pk_mul_f32 v[208:209], v[208:209], v[46:47]
	v_pk_mul_f32 v[214:215], v[214:215], v[246:247]
	v_pk_mul_f32 v[210:211], v[210:211], v[246:247]
	v_add_u32_e32 v47, 64, v217
	s_waitcnt lgkmcnt(2)
	v_mfma_f32_16x16x32_bf16 v[212:215], v[230:233], v[234:237], v[212:215]
	global_load_dword v190, v93, s[52:53]
	s_waitcnt lgkmcnt(1)
	v_mfma_f32_16x16x32_bf16 v[208:211], v[230:233], v[238:241], v[208:211]
	global_load_dword v191, v93, s[52:53] offset:2048
	ds_read_b128 v[230:233], v110
	ds_read_b128 v[234:237], v219
	s_waitcnt lgkmcnt(1)
	v_mfma_f32_16x16x32_bf16 v[208:211], v[242:245], v[230:233], v[208:211]
	global_load_dword v192, v93, s[54:55]
	s_waitcnt lgkmcnt(0)
	v_mfma_f32_16x16x32_bf16 v[212:215], v[242:245], v[234:237], v[212:215]
	global_load_dword v193, v93, s[54:55] offset:2048
	s_nop 5
	v_mov_b32_dpp v46, v208 row_newbcast:0 row_mask:0xf bank_mask:0xf
	s_waitcnt lgkmcnt(0)
	v_max_f32_e64 v46, |v46|, |v46|
	v_max_f32_e32 v207, 1.0, v46
	v_div_scale_f32 v208, s[4:5], v207, v207, v212
	v_rcp_f32_e32 v216, v208
	v_subrev_u32_e32 v46, 64, v222
	v_cndmask_b32_e64 v46, v46, v47, s[2:3]
	v_ashrrev_i32_e32 v47, 31, v46
	v_fma_f32 v218, -v208, v216, 1.0
	v_fmac_f32_e32 v216, v218, v216
	v_div_scale_f32 v218, vcc, v212, v207, v212
	v_mul_f32_e32 v219, v218, v216
	v_fma_f32 v229, -v208, v219, v218
	v_fmac_f32_e32 v219, v229, v216
	v_fma_f32 v208, -v208, v219, v218
	v_div_fmas_f32 v208, v208, v216, v219
	v_div_fixup_f32 v207, v208, v207, v212
	v_mov_b32_dpp v208, v209 row_newbcast:0 row_mask:0xf bank_mask:0xf
	v_lshlrev_b64 v[46:47], 12, v[46:47]
	v_cvt_pk_bf16_f32 v207, v207, s0
	v_lshl_add_u64 v[46:47], v[70:71], 0, v[46:47]
	global_store_short v[46:47], v207, off offset:2048
	s_waitcnt lgkmcnt(0)
	v_max_f32_e64 v47, |v208|, |v208|
	v_max_f32_e32 v207, 1.0, v47
	v_div_scale_f32 v208, s[4:5], v207, v207, v213
	v_rcp_f32_e32 v209, v208
	v_add_u32_e32 v46, 0xffffffbf, v222
	v_add_u32_e32 v47, 0x41, v217
	v_cndmask_b32_e64 v46, v46, v47, s[2:3]
	v_fma_f32 v212, -v208, v209, 1.0
	v_fmac_f32_e32 v209, v212, v209
	v_div_scale_f32 v212, vcc, v213, v207, v213
	v_mul_f32_e32 v216, v212, v209
	v_fma_f32 v218, -v208, v216, v212
	v_fmac_f32_e32 v216, v218, v209
	v_fma_f32 v208, -v208, v216, v212
	v_div_fmas_f32 v208, v208, v209, v216
	v_div_fixup_f32 v207, v208, v207, v213
	v_mov_b32_dpp v208, v210 row_newbcast:0 row_mask:0xf bank_mask:0xf
	v_ashrrev_i32_e32 v47, 31, v46
	v_lshlrev_b64 v[46:47], 12, v[46:47]
	v_cvt_pk_bf16_f32 v207, v207, s0
	v_lshl_add_u64 v[46:47], v[70:71], 0, v[46:47]
	global_store_short v[46:47], v207, off offset:2048
	s_waitcnt lgkmcnt(0)
	v_max_f32_e64 v47, |v208|, |v208|
	v_max_f32_e32 v207, 1.0, v47
	v_div_scale_f32 v208, s[4:5], v207, v207, v214
	v_rcp_f32_e32 v209, v208
	v_add_u32_e32 v46, 0xfbd, v223
	v_add_u32_e32 v47, 0x42, v217
	v_cndmask_b32_e64 v46, v46, v47, s[2:3]
	v_fma_f32 v210, -v208, v209, 1.0
	v_fmac_f32_e32 v209, v210, v209
	v_div_scale_f32 v210, vcc, v214, v207, v214
	v_mul_f32_e32 v212, v210, v209
	v_fma_f32 v213, -v208, v212, v210
	v_fmac_f32_e32 v212, v213, v209
	v_fma_f32 v208, -v208, v212, v210
	v_div_fmas_f32 v208, v208, v209, v212
	v_div_fixup_f32 v207, v208, v207, v214
	v_mov_b32_dpp v208, v211 row_newbcast:0 row_mask:0xf bank_mask:0xf
	v_ashrrev_i32_e32 v47, 31, v46
	v_lshlrev_b64 v[46:47], 12, v[46:47]
	v_cvt_pk_bf16_f32 v207, v207, s0
	v_lshl_add_u64 v[46:47], v[70:71], 0, v[46:47]
	global_store_short v[46:47], v207, off offset:2048
	s_waitcnt lgkmcnt(0)
	v_max_f32_e64 v46, |v208|, |v208|
	ds_read_b128 v[208:211], v224 offset:33792
	v_max_f32_e32 v212, 1.0, v46
	v_mul_f32_e32 v46, 0x3fb8aa3b, v228
	v_exp_f32_e32 v46, v46
	v_add_u32_e32 v207, 0x43, v217
	ds_read_b128 v[216:219], v111
	ds_read_b128 v[228:231], v49 offset:33792
	v_add_u32_e32 v47, 0xfbc, v223
	v_pk_mul_f32 v[44:45], v[44:45], v[46:47] op_sel_hi:[1,0]
	v_pk_mul_f32 v[42:43], v[42:43], v[46:47] op_sel_hi:[1,0]
	ds_read_b128 v[232:235], v225
	v_div_scale_f32 v213, s[4:5], v212, v212, v215
	s_waitcnt lgkmcnt(2)
	v_mfma_f32_16x16x32_bf16 v[42:45], v[208:211], v[216:219], v[42:45]
	global_load_dword v194, v94, s[52:53]
	v_rcp_f32_e32 v214, v213
	v_cndmask_b32_e64 v222, v47, v207, s[2:3]
	v_ashrrev_i32_e32 v223, 31, v222
	s_waitcnt lgkmcnt(0)
	v_mfma_f32_16x16x32_bf16 v[42:45], v[228:231], v[232:235], v[42:45]
	global_load_dword v195, v94, s[52:53] offset:2048
	v_fma_f32 v47, -v213, v214, 1.0
	v_fmac_f32_e32 v214, v47, v214
	v_div_scale_f32 v47, vcc, v215, v212, v215
	v_pk_mul_f32 v[40:41], v[40:41], v[46:47] op_sel_hi:[1,0]
	s_nop 3
	v_cvt_pk_bf16_f32 v208, v42, v43
	v_cvt_pk_bf16_f32 v209, v44, v45
	ds_write_b64 v189, v[208:209]
	ds_read_b128 v[208:211], v49 offset:33792
	ds_read_b128 v[216:219], v224 offset:33792
	ds_read_b128 v[228:231], v226
	ds_read_b128 v[232:235], v227
	v_pk_mul_f32 v[38:39], v[38:39], v[46:47] op_sel_hi:[1,0]
	v_mul_f32_e32 v207, v47, v214
	s_waitcnt lgkmcnt(1)
	v_mfma_f32_16x16x32_bf16 v[38:41], v[216:219], v[228:231], v[38:41]
	global_load_dword v196, v94, s[54:55]
	v_fma_f32 v216, -v213, v207, v47
	v_fmac_f32_e32 v207, v216, v214
	v_fma_f32 v47, -v213, v207, v47
	s_waitcnt lgkmcnt(0)
	v_mfma_f32_16x16x32_bf16 v[38:41], v[208:211], v[232:235], v[38:41]
	global_load_dword v197, v94, s[54:55] offset:2048
	v_div_fmas_f32 v47, v47, v214, v207
	v_div_fixup_f32 v47, v47, v212, v215
	v_cvt_pk_bf16_f32 v47, v47, s0
	v_pk_mul_f32 v[36:37], v[36:37], v[46:47] op_sel_hi:[1,0]
	v_pk_mul_f32 v[34:35], v[34:35], v[46:47] op_sel_hi:[1,0]
	s_nop 2
	v_cvt_pk_bf16_f32 v208, v38, v39
	v_cvt_pk_bf16_f32 v209, v40, v41
	ds_write_b64 v189, v[208:209] offset:8448
	ds_read_b128 v[208:211], v49 offset:33792
	ds_read_b128 v[216:219], v224 offset:33792
	ds_read_b128 v[212:215], v206
	ds_read_b128 v[228:231], v110
	s_waitcnt lgkmcnt(1)
	v_mfma_f32_16x16x32_bf16 v[34:37], v[216:219], v[212:215], v[34:37]
	global_load_dword v198, v95, s[52:53]
	v_lshlrev_b64 v[212:213], 12, v[222:223]
	v_lshl_add_u64 v[212:213], v[70:71], 0, v[212:213]
	global_store_short v[212:213], v47, off offset:2048
	s_waitcnt lgkmcnt(0)
	v_mfma_f32_16x16x32_bf16 v[34:37], v[208:211], v[228:231], v[34:37]
	global_load_dword v199, v95, s[52:53] offset:2048
	s_and_saveexec_b64 s[4:5], s[0:1]
	s_nop 6
	v_cvt_pk_bf16_f32 v208, v34, v35
	v_cvt_pk_bf16_f32 v209, v36, v37
	ds_write_b64 v172, v[208:209] offset:16896
	s_or_b64 exec, exec, s[4:5]
	ds_read_b128 v[208:211], v224 offset:36096
	ds_read_b128 v[212:215], v111
	ds_read_b128 v[216:219], v49 offset:36096
	v_mov_b32_e32 v47, v46
	v_mov_b32_e32 v222, v46
	v_mov_b32_e32 v223, v46
	v_pk_mul_f32 v[28:29], v[28:29], v[222:223]
	v_pk_mul_f32 v[26:27], v[26:27], v[46:47]
	v_pk_mul_f32 v[32:33], v[32:33], v[222:223]
	v_pk_mul_f32 v[30:31], v[30:31], v[46:47]
	s_waitcnt lgkmcnt(1)
	v_mfma_f32_16x16x32_bf16 v[26:29], v[208:211], v[212:215], v[26:29]
	global_load_dword v200, v95, s[54:55]
	ds_read_b128 v[208:211], v225
	v_pk_mul_f32 v[24:25], v[24:25], v[222:223]
	v_pk_mul_f32 v[22:23], v[22:23], v[46:47]
	s_waitcnt lgkmcnt(0)
	v_mfma_f32_16x16x32_bf16 v[26:29], v[216:219], v[208:211], v[26:29]
	global_load_dword v201, v95, s[54:55] offset:2048
	s_nop 7
	v_cvt_pk_bf16_f32 v208, v26, v27
	v_cvt_pk_bf16_f32 v209, v28, v29
	ds_write_b64 v189, v[208:209] offset:32
	ds_read_b128 v[208:211], v224 offset:36096
	ds_read_b128 v[212:215], v226
	ds_read_b128 v[216:219], v49 offset:36096
	ds_read_b128 v[226:229], v227
	s_waitcnt lgkmcnt(2)
	v_mfma_f32_16x16x32_bf16 v[30:33], v[208:211], v[212:215], v[30:33]
	global_load_dword v202, v96, s[52:53]
	s_waitcnt lgkmcnt(0)
	v_mfma_f32_16x16x32_bf16 v[30:33], v[216:219], v[226:229], v[30:33]
	global_load_dword v203, v96, s[52:53] offset:2048
	s_nop 7
	v_cvt_pk_bf16_f32 v208, v30, v31
	v_cvt_pk_bf16_f32 v209, v32, v33
	ds_write_b64 v189, v[208:209] offset:8480
	ds_read_b128 v[208:211], v224 offset:36096
	ds_read_b128 v[212:215], v206
	ds_read_b128 v[216:219], v49 offset:36096
	ds_read_b128 v[222:225], v110
	s_waitcnt lgkmcnt(2)
	v_mfma_f32_16x16x32_bf16 v[22:25], v[208:211], v[212:215], v[22:25]
	global_load_dword v204, v96, s[54:55]
	s_waitcnt lgkmcnt(0)
	v_mfma_f32_16x16x32_bf16 v[22:25], v[216:219], v[222:225], v[22:25]
	global_load_dword v205, v96, s[54:55] offset:2048
	s_add_u32 s52, s52, s56
	s_addc_u32 s53, s53, s57
	s_add_u32 s54, s54, s56
	s_addc_u32 s55, s55, s57
	s_and_saveexec_b64 s[4:5], s[0:1]
	s_cbranch_execz .LBB0_452
	s_nop 5
	v_cvt_pk_bf16_f32 v46, v22, v23
	v_cvt_pk_bf16_f32 v47, v24, v25
	ds_write_b64 v172, v[46:47] offset:16928
	s_branch .LBB0_452
